# K GEMM epilogue: row-major K copy stored 8 bytes per lane after an in-quad 4x4 bf16 transpose (32 stores per lane and unit instead of 128 two-byte stores)
# baseline (speedup 1.0000x reference)
.LBB0_682:
	v_and_b32_e32 v232, 3, v200
	v_mul_u32_u24_e32 v232, 0xffe, v232
	v_mov_b32_e32 v233, 0
	v_and_b32_e32 v234, 1, v200
	v_cmp_eq_u32_e32 vcc, 1, v234
	v_mov_b32_e32 v234, 0x5040100
	v_mov_b32_e32 v235, 0x3020706
	s_nop 0
	v_cndmask_b32_e32 v234, v234, v235, vcc
	s_mov_b32 s80, 0xcccccccc
	s_mov_b32 s81, 0xcccccccc
	v_lshl_add_u32 v142, s20, 8, v149
	v_or_b32_e32 v146, 1, v142
	v_ashrrev_i32_e32 v147, 31, v146
	v_lshlrev_b64 v[158:159], 12, v[146:147]
	v_or_b32_e32 v146, 2, v142
	v_ashrrev_i32_e32 v144, 2, v142
	v_ashrrev_i32_e32 v147, 31, v146
	v_lshl_or_b32 v154, s60, 8, v150
	v_ashrrev_i32_e32 v145, 31, v144
	v_lshlrev_b64 v[160:161], 12, v[146:147]
	v_or_b32_e32 v146, 3, v142
	v_lshlrev_b64 v[144:145], 14, v[144:145]
	v_ashrrev_i32_e32 v147, 31, v146
	v_ashrrev_i32_e32 v155, 31, v154
	v_ashrrev_i32_e32 v143, 31, v142
	v_lshlrev_b64 v[162:163], 12, v[146:147]
	v_lshl_add_u64 v[166:167], s[14:15], 0, v[144:145]
	v_lshlrev_b64 v[146:147], 3, v[154:155]
	v_lshlrev_b64 v[156:157], 12, v[142:143]
	v_lshl_add_u64 v[144:145], v[166:167], 0, v[146:147]
	v_cvt_pk_bf16_f32 v164, v40, v41
	v_cvt_pk_bf16_f32 v165, v42, v43
	flat_store_dwordx2 v[144:145], v[164:165]
	v_lshl_add_u64 v[156:157], s[16:17], 0, v[156:157]
	v_lshlrev_b64 v[144:145], 1, v[154:155]
	v_lshl_add_u64 v[158:159], s[16:17], 0, v[158:159]
	v_lshl_add_u64 v[156:157], v[156:157], 0, v[144:145]
	v_lshl_add_u64 v[158:159], v[158:159], 0, v[144:145]
	v_lshl_add_u64 v[160:161], s[16:17], 0, v[160:161]
	v_lshl_add_u64 v[162:163], s[16:17], 0, v[162:163]
	v_lshl_add_u64 v[242:243], v[156:157], 0, v[232:233]
	s_nop 1
	v_mov_b32_dpp v236, v164 quad_perm:[1,0,3,2] row_mask:0xf bank_mask:0xf
	v_mov_b32_dpp v237, v165 quad_perm:[1,0,3,2] row_mask:0xf bank_mask:0xf
	v_perm_b32 v244, v236, v164, v234
	v_perm_b32 v245, v237, v165, v234
	s_nop 1
	v_mov_b32_dpp v238, v244 quad_perm:[2,3,0,1] row_mask:0xf bank_mask:0xf
	v_mov_b32_dpp v239, v245 quad_perm:[2,3,0,1] row_mask:0xf bank_mask:0xf
	v_cndmask_b32_e64 v240, v244, v239, s[80:81]
	v_cndmask_b32_e64 v241, v238, v245, s[80:81]
	flat_store_dwordx2 v[242:243], v[240:241]
	v_lshl_add_u64 v[160:161], v[160:161], 0, v[144:145]
	v_lshl_add_u64 v[162:163], v[162:163], 0, v[144:145]
	v_or_b32_e32 v164, 16, v154
	v_ashrrev_i32_e32 v165, 31, v164
	v_cvt_pk_bf16_f32 v168, v124, v125
	v_lshlrev_b64 v[124:125], 3, v[164:165]
	v_cvt_pk_bf16_f32 v169, v126, v127
	v_lshl_add_u64 v[126:127], v[166:167], 0, v[124:125]
	flat_store_dwordx2 v[126:127], v[168:169]
	s_nop 1
	v_mov_b32_dpp v236, v168 quad_perm:[1,0,3,2] row_mask:0xf bank_mask:0xf
	v_mov_b32_dpp v237, v169 quad_perm:[1,0,3,2] row_mask:0xf bank_mask:0xf
	v_perm_b32 v244, v236, v168, v234
	v_perm_b32 v245, v237, v169, v234
	s_nop 1
	v_mov_b32_dpp v238, v244 quad_perm:[2,3,0,1] row_mask:0xf bank_mask:0xf
	v_mov_b32_dpp v239, v245 quad_perm:[2,3,0,1] row_mask:0xf bank_mask:0xf
	v_cndmask_b32_e64 v240, v244, v239, s[80:81]
	v_cndmask_b32_e64 v241, v238, v245, s[80:81]
	flat_store_dwordx2 v[242:243], v[240:241] offset:32
	v_or_b32_e32 v126, 0x80, v154
	v_ashrrev_i32_e32 v127, 31, v126
	v_cvt_pk_bf16_f32 v164, v120, v121
	v_lshlrev_b64 v[120:121], 3, v[126:127]
	v_cvt_pk_bf16_f32 v165, v122, v123
	v_lshl_add_u64 v[122:123], v[166:167], 0, v[120:121]
	flat_store_dwordx2 v[122:123], v[164:165]
	s_nop 1
	v_mov_b32_dpp v236, v164 quad_perm:[1,0,3,2] row_mask:0xf bank_mask:0xf
	v_mov_b32_dpp v237, v165 quad_perm:[1,0,3,2] row_mask:0xf bank_mask:0xf
	v_perm_b32 v244, v236, v164, v234
	v_perm_b32 v245, v237, v165, v234
	s_nop 1
	v_mov_b32_dpp v238, v244 quad_perm:[2,3,0,1] row_mask:0xf bank_mask:0xf
	v_mov_b32_dpp v239, v245 quad_perm:[2,3,0,1] row_mask:0xf bank_mask:0xf
	v_cndmask_b32_e64 v240, v244, v239, s[80:81]
	v_cndmask_b32_e64 v241, v238, v245, s[80:81]
	flat_store_dwordx2 v[242:243], v[240:241] offset:256
	v_or_b32_e32 v122, 0x90, v154
	v_ashrrev_i32_e32 v123, 31, v122
	v_cvt_pk_bf16_f32 v126, v116, v117
	v_lshlrev_b64 v[116:117], 3, v[122:123]
	v_cvt_pk_bf16_f32 v127, v118, v119
	v_lshl_add_u64 v[118:119], v[166:167], 0, v[116:117]
	flat_store_dwordx2 v[118:119], v[126:127]
	s_nop 1
	v_mov_b32_dpp v236, v126 quad_perm:[1,0,3,2] row_mask:0xf bank_mask:0xf
	v_mov_b32_dpp v237, v127 quad_perm:[1,0,3,2] row_mask:0xf bank_mask:0xf
	v_perm_b32 v244, v236, v126, v234
	v_perm_b32 v245, v237, v127, v234
	s_nop 1
	v_mov_b32_dpp v238, v244 quad_perm:[2,3,0,1] row_mask:0xf bank_mask:0xf
	v_mov_b32_dpp v239, v245 quad_perm:[2,3,0,1] row_mask:0xf bank_mask:0xf
	v_cndmask_b32_e64 v240, v244, v239, s[80:81]
	v_cndmask_b32_e64 v241, v238, v245, s[80:81]
	flat_store_dwordx2 v[242:243], v[240:241] offset:288
	v_or_b32_e32 v118, 16, v142
	v_ashrrev_i32_e32 v122, 2, v118
	v_or_b32_e32 v126, 17, v142
	v_or_b32_e32 v154, 18, v142
	v_or_b32_e32 v156, 19, v142
	v_ashrrev_i32_e32 v123, 31, v122
	v_ashrrev_i32_e32 v119, 31, v118
	v_ashrrev_i32_e32 v127, 31, v126
	v_ashrrev_i32_e32 v155, 31, v154
	v_ashrrev_i32_e32 v157, 31, v156
	v_lshlrev_b64 v[122:123], 14, v[122:123]
	v_lshlrev_b64 v[118:119], 12, v[118:119]
	v_lshlrev_b64 v[126:127], 12, v[126:127]
	v_lshlrev_b64 v[154:155], 12, v[154:155]
	v_lshlrev_b64 v[156:157], 12, v[156:157]
	v_lshl_add_u64 v[122:123], s[14:15], 0, v[122:123]
	v_lshl_add_u64 v[118:119], s[16:17], 0, v[118:119]
	v_lshl_add_u64 v[126:127], s[16:17], 0, v[126:127]
	v_lshl_add_u64 v[154:155], s[16:17], 0, v[154:155]
	v_lshl_add_u64 v[156:157], s[16:17], 0, v[156:157]
	v_lshl_add_u64 v[160:161], v[122:123], 0, v[146:147]
	v_lshl_add_u64 v[118:119], v[118:119], 0, v[144:145]
	v_lshl_add_u64 v[126:127], v[126:127], 0, v[144:145]
	v_lshl_add_u64 v[154:155], v[154:155], 0, v[144:145]
	v_lshl_add_u64 v[156:157], v[156:157], 0, v[144:145]
	v_cvt_pk_bf16_f32 v158, v36, v37
	v_cvt_pk_bf16_f32 v159, v38, v39
	flat_store_dwordx2 v[160:161], v[158:159]
	v_lshl_add_u64 v[242:243], v[118:119], 0, v[232:233]
	s_nop 1
	v_mov_b32_dpp v236, v158 quad_perm:[1,0,3,2] row_mask:0xf bank_mask:0xf
	v_mov_b32_dpp v237, v159 quad_perm:[1,0,3,2] row_mask:0xf bank_mask:0xf
	v_perm_b32 v244, v236, v158, v234
	v_perm_b32 v245, v237, v159, v234
	s_nop 1
	v_mov_b32_dpp v238, v244 quad_perm:[2,3,0,1] row_mask:0xf bank_mask:0xf
	v_mov_b32_dpp v239, v245 quad_perm:[2,3,0,1] row_mask:0xf bank_mask:0xf
	v_cndmask_b32_e64 v240, v244, v239, s[80:81]
	v_cndmask_b32_e64 v241, v238, v245, s[80:81]
	flat_store_dwordx2 v[242:243], v[240:241]
	v_cvt_pk_bf16_f32 v112, v112, v113
	v_cvt_pk_bf16_f32 v113, v114, v115
	v_lshl_add_u64 v[114:115], v[122:123], 0, v[124:125]
	flat_store_dwordx2 v[114:115], v[112:113]
	s_nop 1
	v_mov_b32_dpp v236, v112 quad_perm:[1,0,3,2] row_mask:0xf bank_mask:0xf
	v_mov_b32_dpp v237, v113 quad_perm:[1,0,3,2] row_mask:0xf bank_mask:0xf
	v_perm_b32 v244, v236, v112, v234
	v_perm_b32 v245, v237, v113, v234
	s_nop 1
	v_mov_b32_dpp v238, v244 quad_perm:[2,3,0,1] row_mask:0xf bank_mask:0xf
	v_mov_b32_dpp v239, v245 quad_perm:[2,3,0,1] row_mask:0xf bank_mask:0xf
	v_cndmask_b32_e64 v240, v244, v239, s[80:81]
	v_cndmask_b32_e64 v241, v238, v245, s[80:81]
	flat_store_dwordx2 v[242:243], v[240:241] offset:32
	v_cvt_pk_bf16_f32 v108, v108, v109
	v_cvt_pk_bf16_f32 v109, v110, v111
	v_lshl_add_u64 v[110:111], v[122:123], 0, v[120:121]
	flat_store_dwordx2 v[110:111], v[108:109]
	s_nop 1
	v_mov_b32_dpp v236, v108 quad_perm:[1,0,3,2] row_mask:0xf bank_mask:0xf
	v_mov_b32_dpp v237, v109 quad_perm:[1,0,3,2] row_mask:0xf bank_mask:0xf
	v_perm_b32 v244, v236, v108, v234
	v_perm_b32 v245, v237, v109, v234
	s_nop 1
	v_mov_b32_dpp v238, v244 quad_perm:[2,3,0,1] row_mask:0xf bank_mask:0xf
	v_mov_b32_dpp v239, v245 quad_perm:[2,3,0,1] row_mask:0xf bank_mask:0xf
	v_cndmask_b32_e64 v240, v244, v239, s[80:81]
	v_cndmask_b32_e64 v241, v238, v245, s[80:81]
	flat_store_dwordx2 v[242:243], v[240:241] offset:256
	v_cvt_pk_bf16_f32 v104, v104, v105
	v_cvt_pk_bf16_f32 v105, v106, v107
	v_lshl_add_u64 v[106:107], v[122:123], 0, v[116:117]
	flat_store_dwordx2 v[106:107], v[104:105]
	s_nop 1
	v_mov_b32_dpp v236, v104 quad_perm:[1,0,3,2] row_mask:0xf bank_mask:0xf
	v_mov_b32_dpp v237, v105 quad_perm:[1,0,3,2] row_mask:0xf bank_mask:0xf
	v_perm_b32 v244, v236, v104, v234
	v_perm_b32 v245, v237, v105, v234
	s_nop 1
	v_mov_b32_dpp v238, v244 quad_perm:[2,3,0,1] row_mask:0xf bank_mask:0xf
	v_mov_b32_dpp v239, v245 quad_perm:[2,3,0,1] row_mask:0xf bank_mask:0xf
	v_cndmask_b32_e64 v240, v244, v239, s[80:81]
	v_cndmask_b32_e64 v241, v238, v245, s[80:81]
	flat_store_dwordx2 v[242:243], v[240:241] offset:288
	v_or_b32_e32 v104, 32, v142
	v_ashrrev_i32_e32 v106, 2, v104
	v_or_b32_e32 v108, 33, v142
	v_or_b32_e32 v110, 34, v142
	v_or_b32_e32 v112, 35, v142
	v_ashrrev_i32_e32 v107, 31, v106
	v_ashrrev_i32_e32 v105, 31, v104
	v_ashrrev_i32_e32 v109, 31, v108
	v_ashrrev_i32_e32 v111, 31, v110
	v_ashrrev_i32_e32 v113, 31, v112
	v_lshlrev_b64 v[106:107], 14, v[106:107]
	v_lshlrev_b64 v[104:105], 12, v[104:105]
	v_lshlrev_b64 v[108:109], 12, v[108:109]
	v_lshlrev_b64 v[110:111], 12, v[110:111]
	v_lshlrev_b64 v[112:113], 12, v[112:113]
	v_lshl_add_u64 v[106:107], s[14:15], 0, v[106:107]
	v_lshl_add_u64 v[104:105], s[16:17], 0, v[104:105]
	v_lshl_add_u64 v[108:109], s[16:17], 0, v[108:109]
	v_lshl_add_u64 v[110:111], s[16:17], 0, v[110:111]
	v_lshl_add_u64 v[112:113], s[16:17], 0, v[112:113]
	v_lshl_add_u64 v[118:119], v[106:107], 0, v[146:147]
	v_lshl_add_u64 v[104:105], v[104:105], 0, v[144:145]
	v_lshl_add_u64 v[108:109], v[108:109], 0, v[144:145]
	v_lshl_add_u64 v[110:111], v[110:111], 0, v[144:145]
	v_lshl_add_u64 v[112:113], v[112:113], 0, v[144:145]
	v_cvt_pk_bf16_f32 v114, v28, v29
	v_cvt_pk_bf16_f32 v115, v30, v31
	flat_store_dwordx2 v[118:119], v[114:115]
	v_lshl_add_u64 v[242:243], v[104:105], 0, v[232:233]
	s_nop 1
	v_mov_b32_dpp v236, v114 quad_perm:[1,0,3,2] row_mask:0xf bank_mask:0xf
	v_mov_b32_dpp v237, v115 quad_perm:[1,0,3,2] row_mask:0xf bank_mask:0xf
	v_perm_b32 v244, v236, v114, v234
	v_perm_b32 v245, v237, v115, v234
	s_nop 1
	v_mov_b32_dpp v238, v244 quad_perm:[2,3,0,1] row_mask:0xf bank_mask:0xf
	v_mov_b32_dpp v239, v245 quad_perm:[2,3,0,1] row_mask:0xf bank_mask:0xf
	v_cndmask_b32_e64 v240, v244, v239, s[80:81]
	v_cndmask_b32_e64 v241, v238, v245, s[80:81]
	flat_store_dwordx2 v[242:243], v[240:241]
	v_cvt_pk_bf16_f32 v100, v100, v101
	v_cvt_pk_bf16_f32 v101, v102, v103
	v_lshl_add_u64 v[102:103], v[106:107], 0, v[124:125]
	flat_store_dwordx2 v[102:103], v[100:101]
	s_nop 1
	v_mov_b32_dpp v236, v100 quad_perm:[1,0,3,2] row_mask:0xf bank_mask:0xf
	v_mov_b32_dpp v237, v101 quad_perm:[1,0,3,2] row_mask:0xf bank_mask:0xf
	v_perm_b32 v244, v236, v100, v234
	v_perm_b32 v245, v237, v101, v234
	s_nop 1
	v_mov_b32_dpp v238, v244 quad_perm:[2,3,0,1] row_mask:0xf bank_mask:0xf
	v_mov_b32_dpp v239, v245 quad_perm:[2,3,0,1] row_mask:0xf bank_mask:0xf
	v_cndmask_b32_e64 v240, v244, v239, s[80:81]
	v_cndmask_b32_e64 v241, v238, v245, s[80:81]
	flat_store_dwordx2 v[242:243], v[240:241] offset:32
	v_cvt_pk_bf16_f32 v96, v96, v97
	v_cvt_pk_bf16_f32 v97, v98, v99
	v_lshl_add_u64 v[98:99], v[106:107], 0, v[120:121]
	flat_store_dwordx2 v[98:99], v[96:97]
	s_nop 1
	v_mov_b32_dpp v236, v96 quad_perm:[1,0,3,2] row_mask:0xf bank_mask:0xf
	v_mov_b32_dpp v237, v97 quad_perm:[1,0,3,2] row_mask:0xf bank_mask:0xf
	v_perm_b32 v244, v236, v96, v234
	v_perm_b32 v245, v237, v97, v234
	s_nop 1
	v_mov_b32_dpp v238, v244 quad_perm:[2,3,0,1] row_mask:0xf bank_mask:0xf
	v_mov_b32_dpp v239, v245 quad_perm:[2,3,0,1] row_mask:0xf bank_mask:0xf
	v_cndmask_b32_e64 v240, v244, v239, s[80:81]
	v_cndmask_b32_e64 v241, v238, v245, s[80:81]
	flat_store_dwordx2 v[242:243], v[240:241] offset:256
	v_cvt_pk_bf16_f32 v92, v92, v93
	v_cvt_pk_bf16_f32 v93, v94, v95
	v_lshl_add_u64 v[94:95], v[106:107], 0, v[116:117]
	flat_store_dwordx2 v[94:95], v[92:93]
	s_nop 1
	v_mov_b32_dpp v236, v92 quad_perm:[1,0,3,2] row_mask:0xf bank_mask:0xf
	v_mov_b32_dpp v237, v93 quad_perm:[1,0,3,2] row_mask:0xf bank_mask:0xf
	v_perm_b32 v244, v236, v92, v234
	v_perm_b32 v245, v237, v93, v234
	s_nop 1
	v_mov_b32_dpp v238, v244 quad_perm:[2,3,0,1] row_mask:0xf bank_mask:0xf
	v_mov_b32_dpp v239, v245 quad_perm:[2,3,0,1] row_mask:0xf bank_mask:0xf
	v_cndmask_b32_e64 v240, v244, v239, s[80:81]
	v_cndmask_b32_e64 v241, v238, v245, s[80:81]
	flat_store_dwordx2 v[242:243], v[240:241] offset:288
	v_or_b32_e32 v92, 48, v142
	v_ashrrev_i32_e32 v94, 2, v92
	v_or_b32_e32 v96, 49, v142
	v_or_b32_e32 v98, 50, v142
	v_or_b32_e32 v100, 51, v142
	v_ashrrev_i32_e32 v95, 31, v94
	v_ashrrev_i32_e32 v93, 31, v92
	v_ashrrev_i32_e32 v97, 31, v96
	v_ashrrev_i32_e32 v99, 31, v98
	v_ashrrev_i32_e32 v101, 31, v100
	v_lshlrev_b64 v[94:95], 14, v[94:95]
	v_lshlrev_b64 v[92:93], 12, v[92:93]
	v_lshlrev_b64 v[96:97], 12, v[96:97]
	v_lshlrev_b64 v[98:99], 12, v[98:99]
	v_lshlrev_b64 v[100:101], 12, v[100:101]
	v_lshl_add_u64 v[94:95], s[14:15], 0, v[94:95]
	v_lshl_add_u64 v[92:93], s[16:17], 0, v[92:93]
	v_lshl_add_u64 v[96:97], s[16:17], 0, v[96:97]
	v_lshl_add_u64 v[98:99], s[16:17], 0, v[98:99]
	v_lshl_add_u64 v[100:101], s[16:17], 0, v[100:101]
	v_lshl_add_u64 v[104:105], v[94:95], 0, v[146:147]
	v_lshl_add_u64 v[92:93], v[92:93], 0, v[144:145]
	v_lshl_add_u64 v[96:97], v[96:97], 0, v[144:145]
	v_lshl_add_u64 v[98:99], v[98:99], 0, v[144:145]
	v_lshl_add_u64 v[100:101], v[100:101], 0, v[144:145]
	v_cvt_pk_bf16_f32 v102, v24, v25
	v_cvt_pk_bf16_f32 v103, v26, v27
	flat_store_dwordx2 v[104:105], v[102:103]
	v_lshl_add_u64 v[242:243], v[92:93], 0, v[232:233]
	s_nop 1
	v_mov_b32_dpp v236, v102 quad_perm:[1,0,3,2] row_mask:0xf bank_mask:0xf
	v_mov_b32_dpp v237, v103 quad_perm:[1,0,3,2] row_mask:0xf bank_mask:0xf
	v_perm_b32 v244, v236, v102, v234
	v_perm_b32 v245, v237, v103, v234
	s_nop 1
	v_mov_b32_dpp v238, v244 quad_perm:[2,3,0,1] row_mask:0xf bank_mask:0xf
	v_mov_b32_dpp v239, v245 quad_perm:[2,3,0,1] row_mask:0xf bank_mask:0xf
	v_cndmask_b32_e64 v240, v244, v239, s[80:81]
	v_cndmask_b32_e64 v241, v238, v245, s[80:81]
	flat_store_dwordx2 v[242:243], v[240:241]
	v_cvt_pk_bf16_f32 v88, v88, v89
	v_cvt_pk_bf16_f32 v89, v90, v91
	v_lshl_add_u64 v[90:91], v[94:95], 0, v[124:125]
	flat_store_dwordx2 v[90:91], v[88:89]
	s_nop 1
	v_mov_b32_dpp v236, v88 quad_perm:[1,0,3,2] row_mask:0xf bank_mask:0xf
	v_mov_b32_dpp v237, v89 quad_perm:[1,0,3,2] row_mask:0xf bank_mask:0xf
	v_perm_b32 v244, v236, v88, v234
	v_perm_b32 v245, v237, v89, v234
	s_nop 1
	v_mov_b32_dpp v238, v244 quad_perm:[2,3,0,1] row_mask:0xf bank_mask:0xf
	v_mov_b32_dpp v239, v245 quad_perm:[2,3,0,1] row_mask:0xf bank_mask:0xf
	v_cndmask_b32_e64 v240, v244, v239, s[80:81]
	v_cndmask_b32_e64 v241, v238, v245, s[80:81]
	flat_store_dwordx2 v[242:243], v[240:241] offset:32
	v_cvt_pk_bf16_f32 v84, v84, v85
	v_cvt_pk_bf16_f32 v85, v86, v87
	v_lshl_add_u64 v[86:87], v[94:95], 0, v[120:121]
	flat_store_dwordx2 v[86:87], v[84:85]
	s_nop 1
	v_mov_b32_dpp v236, v84 quad_perm:[1,0,3,2] row_mask:0xf bank_mask:0xf
	v_mov_b32_dpp v237, v85 quad_perm:[1,0,3,2] row_mask:0xf bank_mask:0xf
	v_perm_b32 v244, v236, v84, v234
	v_perm_b32 v245, v237, v85, v234
	s_nop 1
	v_mov_b32_dpp v238, v244 quad_perm:[2,3,0,1] row_mask:0xf bank_mask:0xf
	v_mov_b32_dpp v239, v245 quad_perm:[2,3,0,1] row_mask:0xf bank_mask:0xf
	v_cndmask_b32_e64 v240, v244, v239, s[80:81]
	v_cndmask_b32_e64 v241, v238, v245, s[80:81]
	flat_store_dwordx2 v[242:243], v[240:241] offset:256
	v_cvt_pk_bf16_f32 v80, v80, v81
	v_cvt_pk_bf16_f32 v81, v82, v83
	v_lshl_add_u64 v[82:83], v[94:95], 0, v[116:117]
	flat_store_dwordx2 v[82:83], v[80:81]
	s_nop 1
	v_mov_b32_dpp v236, v80 quad_perm:[1,0,3,2] row_mask:0xf bank_mask:0xf
	v_mov_b32_dpp v237, v81 quad_perm:[1,0,3,2] row_mask:0xf bank_mask:0xf
	v_perm_b32 v244, v236, v80, v234
	v_perm_b32 v245, v237, v81, v234
	s_nop 1
	v_mov_b32_dpp v238, v244 quad_perm:[2,3,0,1] row_mask:0xf bank_mask:0xf
	v_mov_b32_dpp v239, v245 quad_perm:[2,3,0,1] row_mask:0xf bank_mask:0xf
	v_cndmask_b32_e64 v240, v244, v239, s[80:81]
	v_cndmask_b32_e64 v241, v238, v245, s[80:81]
	flat_store_dwordx2 v[242:243], v[240:241] offset:288
	v_add_u32_e32 v80, 0x80, v142
	v_ashrrev_i32_e32 v82, 2, v80
	v_add_u32_e32 v84, 0x81, v142
	v_add_u32_e32 v86, 0x82, v142
	v_add_u32_e32 v88, 0x83, v142
	v_ashrrev_i32_e32 v83, 31, v82
	v_ashrrev_i32_e32 v81, 31, v80
	v_ashrrev_i32_e32 v85, 31, v84
	v_ashrrev_i32_e32 v87, 31, v86
	v_ashrrev_i32_e32 v89, 31, v88
	v_lshlrev_b64 v[82:83], 14, v[82:83]
	v_lshlrev_b64 v[80:81], 12, v[80:81]
	v_lshlrev_b64 v[84:85], 12, v[84:85]
	v_lshlrev_b64 v[86:87], 12, v[86:87]
	v_lshlrev_b64 v[88:89], 12, v[88:89]
	v_lshl_add_u64 v[82:83], s[14:15], 0, v[82:83]
	v_lshl_add_u64 v[80:81], s[16:17], 0, v[80:81]
	v_lshl_add_u64 v[84:85], s[16:17], 0, v[84:85]
	v_lshl_add_u64 v[86:87], s[16:17], 0, v[86:87]
	v_lshl_add_u64 v[88:89], s[16:17], 0, v[88:89]
	v_lshl_add_u64 v[92:93], v[82:83], 0, v[146:147]
	v_lshl_add_u64 v[80:81], v[80:81], 0, v[144:145]
	v_lshl_add_u64 v[84:85], v[84:85], 0, v[144:145]
	v_lshl_add_u64 v[86:87], v[86:87], 0, v[144:145]
	v_lshl_add_u64 v[88:89], v[88:89], 0, v[144:145]
	v_cvt_pk_bf16_f32 v90, v12, v13
	v_cvt_pk_bf16_f32 v91, v14, v15
	flat_store_dwordx2 v[92:93], v[90:91]
	v_lshl_add_u64 v[242:243], v[80:81], 0, v[232:233]
	s_nop 1
	v_mov_b32_dpp v236, v90 quad_perm:[1,0,3,2] row_mask:0xf bank_mask:0xf
	v_mov_b32_dpp v237, v91 quad_perm:[1,0,3,2] row_mask:0xf bank_mask:0xf
	v_perm_b32 v244, v236, v90, v234
	v_perm_b32 v245, v237, v91, v234
	s_nop 1
	v_mov_b32_dpp v238, v244 quad_perm:[2,3,0,1] row_mask:0xf bank_mask:0xf
	v_mov_b32_dpp v239, v245 quad_perm:[2,3,0,1] row_mask:0xf bank_mask:0xf
	v_cndmask_b32_e64 v240, v244, v239, s[80:81]
	v_cndmask_b32_e64 v241, v238, v245, s[80:81]
	flat_store_dwordx2 v[242:243], v[240:241]
	v_cvt_pk_bf16_f32 v76, v76, v77
	v_cvt_pk_bf16_f32 v77, v78, v79
	v_lshl_add_u64 v[78:79], v[82:83], 0, v[124:125]
	flat_store_dwordx2 v[78:79], v[76:77]
	s_nop 1
	v_mov_b32_dpp v236, v76 quad_perm:[1,0,3,2] row_mask:0xf bank_mask:0xf
	v_mov_b32_dpp v237, v77 quad_perm:[1,0,3,2] row_mask:0xf bank_mask:0xf
	v_perm_b32 v244, v236, v76, v234
	v_perm_b32 v245, v237, v77, v234
	s_nop 1
	v_mov_b32_dpp v238, v244 quad_perm:[2,3,0,1] row_mask:0xf bank_mask:0xf
	v_mov_b32_dpp v239, v245 quad_perm:[2,3,0,1] row_mask:0xf bank_mask:0xf
	v_cndmask_b32_e64 v240, v244, v239, s[80:81]
	v_cndmask_b32_e64 v241, v238, v245, s[80:81]
	flat_store_dwordx2 v[242:243], v[240:241] offset:32
	v_cvt_pk_bf16_f32 v72, v72, v73
	v_cvt_pk_bf16_f32 v73, v74, v75
	v_lshl_add_u64 v[74:75], v[82:83], 0, v[120:121]
	flat_store_dwordx2 v[74:75], v[72:73]
	s_nop 1
	v_mov_b32_dpp v236, v72 quad_perm:[1,0,3,2] row_mask:0xf bank_mask:0xf
	v_mov_b32_dpp v237, v73 quad_perm:[1,0,3,2] row_mask:0xf bank_mask:0xf
	v_perm_b32 v244, v236, v72, v234
	v_perm_b32 v245, v237, v73, v234
	s_nop 1
	v_mov_b32_dpp v238, v244 quad_perm:[2,3,0,1] row_mask:0xf bank_mask:0xf
	v_mov_b32_dpp v239, v245 quad_perm:[2,3,0,1] row_mask:0xf bank_mask:0xf
	v_cndmask_b32_e64 v240, v244, v239, s[80:81]
	v_cndmask_b32_e64 v241, v238, v245, s[80:81]
	flat_store_dwordx2 v[242:243], v[240:241] offset:256
	v_cvt_pk_bf16_f32 v68, v68, v69
	v_cvt_pk_bf16_f32 v69, v70, v71
	v_lshl_add_u64 v[70:71], v[82:83], 0, v[116:117]
	flat_store_dwordx2 v[70:71], v[68:69]
	s_nop 1
	v_mov_b32_dpp v236, v68 quad_perm:[1,0,3,2] row_mask:0xf bank_mask:0xf
	v_mov_b32_dpp v237, v69 quad_perm:[1,0,3,2] row_mask:0xf bank_mask:0xf
	v_perm_b32 v244, v236, v68, v234
	v_perm_b32 v245, v237, v69, v234
	s_nop 1
	v_mov_b32_dpp v238, v244 quad_perm:[2,3,0,1] row_mask:0xf bank_mask:0xf
	v_mov_b32_dpp v239, v245 quad_perm:[2,3,0,1] row_mask:0xf bank_mask:0xf
	v_cndmask_b32_e64 v240, v244, v239, s[80:81]
	v_cndmask_b32_e64 v241, v238, v245, s[80:81]
	flat_store_dwordx2 v[242:243], v[240:241] offset:288
	v_add_u32_e32 v68, 0x90, v142
	v_ashrrev_i32_e32 v70, 2, v68
	v_add_u32_e32 v72, 0x91, v142
	v_add_u32_e32 v74, 0x92, v142
	v_add_u32_e32 v76, 0x93, v142
	v_ashrrev_i32_e32 v71, 31, v70
	v_ashrrev_i32_e32 v69, 31, v68
	v_ashrrev_i32_e32 v73, 31, v72
	v_ashrrev_i32_e32 v75, 31, v74
	v_ashrrev_i32_e32 v77, 31, v76
	v_lshlrev_b64 v[70:71], 14, v[70:71]
	v_lshlrev_b64 v[68:69], 12, v[68:69]
	v_lshlrev_b64 v[72:73], 12, v[72:73]
	v_lshlrev_b64 v[74:75], 12, v[74:75]
	v_lshlrev_b64 v[76:77], 12, v[76:77]
	v_lshl_add_u64 v[70:71], s[14:15], 0, v[70:71]
	v_lshl_add_u64 v[68:69], s[16:17], 0, v[68:69]
	v_lshl_add_u64 v[72:73], s[16:17], 0, v[72:73]
	v_lshl_add_u64 v[74:75], s[16:17], 0, v[74:75]
	v_lshl_add_u64 v[76:77], s[16:17], 0, v[76:77]
	v_lshl_add_u64 v[80:81], v[70:71], 0, v[146:147]
	v_lshl_add_u64 v[68:69], v[68:69], 0, v[144:145]
	v_lshl_add_u64 v[72:73], v[72:73], 0, v[144:145]
	v_lshl_add_u64 v[74:75], v[74:75], 0, v[144:145]
	v_lshl_add_u64 v[76:77], v[76:77], 0, v[144:145]
	v_cvt_pk_bf16_f32 v78, v8, v9
	v_cvt_pk_bf16_f32 v79, v10, v11
	flat_store_dwordx2 v[80:81], v[78:79]
	v_lshl_add_u64 v[242:243], v[68:69], 0, v[232:233]
	s_nop 1
	v_mov_b32_dpp v236, v78 quad_perm:[1,0,3,2] row_mask:0xf bank_mask:0xf
	v_mov_b32_dpp v237, v79 quad_perm:[1,0,3,2] row_mask:0xf bank_mask:0xf
	v_perm_b32 v244, v236, v78, v234
	v_perm_b32 v245, v237, v79, v234
	s_nop 1
	v_mov_b32_dpp v238, v244 quad_perm:[2,3,0,1] row_mask:0xf bank_mask:0xf
	v_mov_b32_dpp v239, v245 quad_perm:[2,3,0,1] row_mask:0xf bank_mask:0xf
	v_cndmask_b32_e64 v240, v244, v239, s[80:81]
	v_cndmask_b32_e64 v241, v238, v245, s[80:81]
	flat_store_dwordx2 v[242:243], v[240:241]
	v_cvt_pk_bf16_f32 v64, v64, v65
	v_cvt_pk_bf16_f32 v65, v66, v67
	v_lshl_add_u64 v[66:67], v[70:71], 0, v[124:125]
	flat_store_dwordx2 v[66:67], v[64:65]
	s_nop 1
	v_mov_b32_dpp v236, v64 quad_perm:[1,0,3,2] row_mask:0xf bank_mask:0xf
	v_mov_b32_dpp v237, v65 quad_perm:[1,0,3,2] row_mask:0xf bank_mask:0xf
	v_perm_b32 v244, v236, v64, v234
	v_perm_b32 v245, v237, v65, v234
	s_nop 1
	v_mov_b32_dpp v238, v244 quad_perm:[2,3,0,1] row_mask:0xf bank_mask:0xf
	v_mov_b32_dpp v239, v245 quad_perm:[2,3,0,1] row_mask:0xf bank_mask:0xf
	v_cndmask_b32_e64 v240, v244, v239, s[80:81]
	v_cndmask_b32_e64 v241, v238, v245, s[80:81]
	flat_store_dwordx2 v[242:243], v[240:241] offset:32
	v_cvt_pk_bf16_f32 v60, v60, v61
	v_cvt_pk_bf16_f32 v61, v62, v63
	v_lshl_add_u64 v[62:63], v[70:71], 0, v[120:121]
	flat_store_dwordx2 v[62:63], v[60:61]
	s_nop 1
	v_mov_b32_dpp v236, v60 quad_perm:[1,0,3,2] row_mask:0xf bank_mask:0xf
	v_mov_b32_dpp v237, v61 quad_perm:[1,0,3,2] row_mask:0xf bank_mask:0xf
	v_perm_b32 v244, v236, v60, v234
	v_perm_b32 v245, v237, v61, v234
	s_nop 1
	v_mov_b32_dpp v238, v244 quad_perm:[2,3,0,1] row_mask:0xf bank_mask:0xf
	v_mov_b32_dpp v239, v245 quad_perm:[2,3,0,1] row_mask:0xf bank_mask:0xf
	v_cndmask_b32_e64 v240, v244, v239, s[80:81]
	v_cndmask_b32_e64 v241, v238, v245, s[80:81]
	flat_store_dwordx2 v[242:243], v[240:241] offset:256
	v_cvt_pk_bf16_f32 v56, v56, v57
	v_cvt_pk_bf16_f32 v57, v58, v59
	v_lshl_add_u64 v[58:59], v[70:71], 0, v[116:117]
	flat_store_dwordx2 v[58:59], v[56:57]
	s_nop 1
	v_mov_b32_dpp v236, v56 quad_perm:[1,0,3,2] row_mask:0xf bank_mask:0xf
	v_mov_b32_dpp v237, v57 quad_perm:[1,0,3,2] row_mask:0xf bank_mask:0xf
	v_perm_b32 v244, v236, v56, v234
	v_perm_b32 v245, v237, v57, v234
	s_nop 1
	v_mov_b32_dpp v238, v244 quad_perm:[2,3,0,1] row_mask:0xf bank_mask:0xf
	v_mov_b32_dpp v239, v245 quad_perm:[2,3,0,1] row_mask:0xf bank_mask:0xf
	v_cndmask_b32_e64 v240, v244, v239, s[80:81]
	v_cndmask_b32_e64 v241, v238, v245, s[80:81]
	flat_store_dwordx2 v[242:243], v[240:241] offset:288
	v_add_u32_e32 v56, 0xa0, v142
	v_ashrrev_i32_e32 v58, 2, v56
	v_add_u32_e32 v60, 0xa1, v142
	v_add_u32_e32 v62, 0xa2, v142
	v_add_u32_e32 v64, 0xa3, v142
	v_ashrrev_i32_e32 v59, 31, v58
	v_ashrrev_i32_e32 v57, 31, v56
	v_ashrrev_i32_e32 v61, 31, v60
	v_ashrrev_i32_e32 v63, 31, v62
	v_ashrrev_i32_e32 v65, 31, v64
	v_lshlrev_b64 v[58:59], 14, v[58:59]
	v_lshlrev_b64 v[56:57], 12, v[56:57]
	v_lshlrev_b64 v[60:61], 12, v[60:61]
	v_lshlrev_b64 v[62:63], 12, v[62:63]
	v_lshlrev_b64 v[64:65], 12, v[64:65]
	v_lshl_add_u64 v[58:59], s[14:15], 0, v[58:59]
	v_lshl_add_u64 v[56:57], s[16:17], 0, v[56:57]
	v_lshl_add_u64 v[60:61], s[16:17], 0, v[60:61]
	v_lshl_add_u64 v[62:63], s[16:17], 0, v[62:63]
	v_lshl_add_u64 v[64:65], s[16:17], 0, v[64:65]
	v_lshl_add_u64 v[68:69], v[58:59], 0, v[146:147]
	v_lshl_add_u64 v[56:57], v[56:57], 0, v[144:145]
	v_lshl_add_u64 v[60:61], v[60:61], 0, v[144:145]
	v_lshl_add_u64 v[62:63], v[62:63], 0, v[144:145]
	v_lshl_add_u64 v[64:65], v[64:65], 0, v[144:145]
	v_cvt_pk_bf16_f32 v66, v4, v5
	v_cvt_pk_bf16_f32 v67, v6, v7
	flat_store_dwordx2 v[68:69], v[66:67]
	v_lshl_add_u64 v[242:243], v[56:57], 0, v[232:233]
	s_nop 1
	v_mov_b32_dpp v236, v66 quad_perm:[1,0,3,2] row_mask:0xf bank_mask:0xf
	v_mov_b32_dpp v237, v67 quad_perm:[1,0,3,2] row_mask:0xf bank_mask:0xf
	v_perm_b32 v244, v236, v66, v234
	v_perm_b32 v245, v237, v67, v234
	s_nop 1
	v_mov_b32_dpp v238, v244 quad_perm:[2,3,0,1] row_mask:0xf bank_mask:0xf
	v_mov_b32_dpp v239, v245 quad_perm:[2,3,0,1] row_mask:0xf bank_mask:0xf
	v_cndmask_b32_e64 v240, v244, v239, s[80:81]
	v_cndmask_b32_e64 v241, v238, v245, s[80:81]
	flat_store_dwordx2 v[242:243], v[240:241]
	v_cvt_pk_bf16_f32 v52, v52, v53
	v_cvt_pk_bf16_f32 v53, v54, v55
	v_lshl_add_u64 v[54:55], v[58:59], 0, v[124:125]
	flat_store_dwordx2 v[54:55], v[52:53]
	s_nop 1
	v_mov_b32_dpp v236, v52 quad_perm:[1,0,3,2] row_mask:0xf bank_mask:0xf
	v_mov_b32_dpp v237, v53 quad_perm:[1,0,3,2] row_mask:0xf bank_mask:0xf
	v_perm_b32 v244, v236, v52, v234
	v_perm_b32 v245, v237, v53, v234
	s_nop 1
	v_mov_b32_dpp v238, v244 quad_perm:[2,3,0,1] row_mask:0xf bank_mask:0xf
	v_mov_b32_dpp v239, v245 quad_perm:[2,3,0,1] row_mask:0xf bank_mask:0xf
	v_cndmask_b32_e64 v240, v244, v239, s[80:81]
	v_cndmask_b32_e64 v241, v238, v245, s[80:81]
	flat_store_dwordx2 v[242:243], v[240:241] offset:32
	v_cvt_pk_bf16_f32 v48, v48, v49
	v_cvt_pk_bf16_f32 v49, v50, v51
	v_lshl_add_u64 v[50:51], v[58:59], 0, v[120:121]
	flat_store_dwordx2 v[50:51], v[48:49]
	s_nop 1
	v_mov_b32_dpp v236, v48 quad_perm:[1,0,3,2] row_mask:0xf bank_mask:0xf
	v_mov_b32_dpp v237, v49 quad_perm:[1,0,3,2] row_mask:0xf bank_mask:0xf
	v_perm_b32 v244, v236, v48, v234
	v_perm_b32 v245, v237, v49, v234
	s_nop 1
	v_mov_b32_dpp v238, v244 quad_perm:[2,3,0,1] row_mask:0xf bank_mask:0xf
	v_mov_b32_dpp v239, v245 quad_perm:[2,3,0,1] row_mask:0xf bank_mask:0xf
	v_cndmask_b32_e64 v240, v244, v239, s[80:81]
	v_cndmask_b32_e64 v241, v238, v245, s[80:81]
	flat_store_dwordx2 v[242:243], v[240:241] offset:256
	v_cvt_pk_bf16_f32 v44, v44, v45
	v_cvt_pk_bf16_f32 v45, v46, v47
	v_lshl_add_u64 v[46:47], v[58:59], 0, v[116:117]
	flat_store_dwordx2 v[46:47], v[44:45]
	s_nop 1
	v_mov_b32_dpp v236, v44 quad_perm:[1,0,3,2] row_mask:0xf bank_mask:0xf
	v_mov_b32_dpp v237, v45 quad_perm:[1,0,3,2] row_mask:0xf bank_mask:0xf
	v_perm_b32 v244, v236, v44, v234
	v_perm_b32 v245, v237, v45, v234
	s_nop 1
	v_mov_b32_dpp v238, v244 quad_perm:[2,3,0,1] row_mask:0xf bank_mask:0xf
	v_mov_b32_dpp v239, v245 quad_perm:[2,3,0,1] row_mask:0xf bank_mask:0xf
	v_cndmask_b32_e64 v240, v244, v239, s[80:81]
	v_cndmask_b32_e64 v241, v238, v245, s[80:81]
	flat_store_dwordx2 v[242:243], v[240:241] offset:288
	v_add_u32_e32 v44, 0xb0, v142
	v_ashrrev_i32_e32 v46, 2, v44
	v_add_u32_e32 v48, 0xb1, v142
	v_add_u32_e32 v50, 0xb2, v142
	v_add_u32_e32 v52, 0xb3, v142
	v_ashrrev_i32_e32 v47, 31, v46
	v_ashrrev_i32_e32 v45, 31, v44
	v_ashrrev_i32_e32 v49, 31, v48
	v_ashrrev_i32_e32 v51, 31, v50
	v_ashrrev_i32_e32 v53, 31, v52
	v_lshlrev_b64 v[46:47], 14, v[46:47]
	v_lshlrev_b64 v[44:45], 12, v[44:45]
	v_lshlrev_b64 v[48:49], 12, v[48:49]
	v_lshlrev_b64 v[50:51], 12, v[50:51]
	v_lshlrev_b64 v[52:53], 12, v[52:53]
	v_lshl_add_u64 v[46:47], s[14:15], 0, v[46:47]
	v_lshl_add_u64 v[44:45], s[16:17], 0, v[44:45]
	v_lshl_add_u64 v[48:49], s[16:17], 0, v[48:49]
	v_lshl_add_u64 v[50:51], s[16:17], 0, v[50:51]
	v_lshl_add_u64 v[52:53], s[16:17], 0, v[52:53]
	v_lshl_add_u64 v[56:57], v[46:47], 0, v[146:147]
	v_lshl_add_u64 v[44:45], v[44:45], 0, v[144:145]
	v_lshl_add_u64 v[48:49], v[48:49], 0, v[144:145]
	v_lshl_add_u64 v[50:51], v[50:51], 0, v[144:145]
	v_lshl_add_u64 v[52:53], v[52:53], 0, v[144:145]
	v_cvt_pk_bf16_f32 v54, v0, v1
	v_cvt_pk_bf16_f32 v55, v2, v3
	flat_store_dwordx2 v[56:57], v[54:55]
	v_lshl_add_u64 v[242:243], v[44:45], 0, v[232:233]
	s_nop 1
	v_mov_b32_dpp v236, v54 quad_perm:[1,0,3,2] row_mask:0xf bank_mask:0xf
	v_mov_b32_dpp v237, v55 quad_perm:[1,0,3,2] row_mask:0xf bank_mask:0xf
	v_perm_b32 v244, v236, v54, v234
	v_perm_b32 v245, v237, v55, v234
	s_nop 1
	v_mov_b32_dpp v238, v244 quad_perm:[2,3,0,1] row_mask:0xf bank_mask:0xf
	v_mov_b32_dpp v239, v245 quad_perm:[2,3,0,1] row_mask:0xf bank_mask:0xf
	v_cndmask_b32_e64 v240, v244, v239, s[80:81]
	v_cndmask_b32_e64 v241, v238, v245, s[80:81]
	flat_store_dwordx2 v[242:243], v[240:241]
	v_cvt_pk_bf16_f32 v32, v32, v33
	v_cvt_pk_bf16_f32 v33, v34, v35
	v_lshl_add_u64 v[34:35], v[46:47], 0, v[124:125]
	flat_store_dwordx2 v[34:35], v[32:33]
	s_nop 1
	v_mov_b32_dpp v236, v32 quad_perm:[1,0,3,2] row_mask:0xf bank_mask:0xf
	v_mov_b32_dpp v237, v33 quad_perm:[1,0,3,2] row_mask:0xf bank_mask:0xf
	v_perm_b32 v244, v236, v32, v234
	v_perm_b32 v245, v237, v33, v234
	s_nop 1
	v_mov_b32_dpp v238, v244 quad_perm:[2,3,0,1] row_mask:0xf bank_mask:0xf
	v_mov_b32_dpp v239, v245 quad_perm:[2,3,0,1] row_mask:0xf bank_mask:0xf
	v_cndmask_b32_e64 v240, v244, v239, s[80:81]
	v_cndmask_b32_e64 v241, v238, v245, s[80:81]
	flat_store_dwordx2 v[242:243], v[240:241] offset:32
	v_cvt_pk_bf16_f32 v20, v20, v21
	v_cvt_pk_bf16_f32 v21, v22, v23
	v_lshl_add_u64 v[22:23], v[46:47], 0, v[120:121]
	flat_store_dwordx2 v[22:23], v[20:21]
	s_nop 1
	v_mov_b32_dpp v236, v20 quad_perm:[1,0,3,2] row_mask:0xf bank_mask:0xf
	v_mov_b32_dpp v237, v21 quad_perm:[1,0,3,2] row_mask:0xf bank_mask:0xf
	v_perm_b32 v244, v236, v20, v234
	v_perm_b32 v245, v237, v21, v234
	s_nop 1
	v_mov_b32_dpp v238, v244 quad_perm:[2,3,0,1] row_mask:0xf bank_mask:0xf
	v_mov_b32_dpp v239, v245 quad_perm:[2,3,0,1] row_mask:0xf bank_mask:0xf
	v_cndmask_b32_e64 v240, v244, v239, s[80:81]
	v_cndmask_b32_e64 v241, v238, v245, s[80:81]
	flat_store_dwordx2 v[242:243], v[240:241] offset:256
	v_cvt_pk_bf16_f32 v16, v16, v17
	v_cvt_pk_bf16_f32 v17, v18, v19
	v_lshl_add_u64 v[18:19], v[46:47], 0, v[116:117]
	flat_store_dwordx2 v[18:19], v[16:17]
	s_nop 1
	v_mov_b32_dpp v236, v16 quad_perm:[1,0,3,2] row_mask:0xf bank_mask:0xf
	v_mov_b32_dpp v237, v17 quad_perm:[1,0,3,2] row_mask:0xf bank_mask:0xf
	v_perm_b32 v244, v236, v16, v234
	v_perm_b32 v245, v237, v17, v234
	s_nop 1
	v_mov_b32_dpp v238, v244 quad_perm:[2,3,0,1] row_mask:0xf bank_mask:0xf
	v_mov_b32_dpp v239, v245 quad_perm:[2,3,0,1] row_mask:0xf bank_mask:0xf
	v_cndmask_b32_e64 v240, v244, v239, s[80:81]
	v_cndmask_b32_e64 v241, v238, v245, s[80:81]
	flat_store_dwordx2 v[242:243], v[240:241] offset:288
	s_cbranch_execnz .LBB0_680
